# v66 + s4 order interleaved: odd workgroups run their latent attention unit first and their HGRN pass-C block second (even ones keep pass C first)
# speedup vs baseline: 1.0087x; 1.0023x over previous
.LBB0_336:
	s_and_b64 vcc, exec, s[0:1]
	s_cbranch_vccz .LBB0_376
	v_readlane_b32 s0, v255, 16
	v_readlane_b32 s1, v255, 17
	s_and_b64 s[0:1], s[0:1], exec
	s_movk_i32 s0, 0x220
	s_cselect_b32 s8, s0, 0x200
	s_sub_i32 s0, s94, 32
	s_cmp_lt_u32 s0, 10
	v_readlane_b32 s0, v254, 28
	s_cselect_b64 s[18:19], -1, 0
	v_readlane_b32 s1, v254, 29
	s_add_u32 s28, s0, 0x19300000
	s_addc_u32 s29, s1, 0
	v_readlane_b32 s2, v255, 7
	s_add_u32 s36, s0, 0x16f00000
	v_readlane_b32 s3, v255, 8
	s_addc_u32 s37, s1, 0
	s_lshl_b64 s[2:3], s[2:3], 2
	s_add_u32 s42, s0, s2
	v_writelane_b32 v255, s2, 18
	s_addc_u32 s43, s1, s3
	s_add_u32 s9, s0, 0xb200600
	s_addc_u32 s10, s1, 0
	v_writelane_b32 v255, s3, 19
	s_add_u32 s2, s0, 0x2800
	s_addc_u32 s3, s1, 0
	v_writelane_b32 v255, s2, 20
	s_nop 1
	v_writelane_b32 v255, s3, 21
	s_add_u32 s2, s0, 0xa000000
	s_addc_u32 s3, s1, 0
	v_writelane_b32 v255, s2, 22
	s_nop 1
	v_writelane_b32 v255, s3, 23
	s_add_u32 s2, s0, 0x19301100
	s_addc_u32 s3, s1, 0
	v_writelane_b32 v255, s2, 24
	s_add_u32 s46, s0, 0x19300100
	s_addc_u32 s47, s1, 0
	v_writelane_b32 v255, s3, 25
	v_writelane_b32 v255, s18, 26
	s_nop 1
	v_writelane_b32 v255, s19, 27
	v_writelane_b32 v255, s28, 28
	s_nop 1
	v_writelane_b32 v255, s29, 29
	v_writelane_b32 v255, s36, 30
	s_nop 1
	v_writelane_b32 v255, s37, 31
	v_writelane_b32 v255, s42, 32
	s_nop 1
	v_writelane_b32 v255, s43, 33
	v_writelane_b32 v255, s9, 34
	v_writelane_b32 v255, s10, 36
	v_writelane_b32 v255, s46, 38
	s_nop 1
	v_writelane_b32 v255, s47, 39
	v_readlane_b32 s100, v252, 8
	s_and_b32 s101, s100, 1
	s_lshl_b32 s101, s101, 8
	s_add_i32 s100, s100, s101
	s_branch .LBB0_341

.LBB0_345:
	s_or_b64 exec, exec, s[2:3]
	s_waitcnt vmcnt(0) lgkmcnt(0)
	s_barrier
	ds_read_b32 v0, v161 offset:8
	s_mov_b64 s[2:3], -1
	s_waitcnt lgkmcnt(0)
	s_barrier
	v_cmp_le_i32_e32 vcc, s8, v0
	v_readfirstlane_b32 s4, v0
	v_readlane_b32 s101, v252, 8
	s_bitcmp1_b32 s101, 0
	s_cbranch_scc1 .Ls4_odd
	v_readlane_b32 s101, v252, 8
	s_lshr_b32 s100, s101, 5
	s_lshl_b32 s100, s100, 2
	s_bfe_u32 s101, s101, 0x20001
	s_or_b32 s100, s100, s101
	s_addk_i32 s100, 0x200
	v_readlane_b32 s101, v252, 8
	s_and_b32 s101, s101, 0x19
	s_cmp_eq_u32 s101, 0
	s_cselect_b32 s100, s100, 0x7fffffff
	s_cmpk_lt_u32 s4, 0x200
	s_cselect_b32 s100, s100, 0x7fffffff
	v_readlane_b32 s101, v252, 8
	s_addk_i32 s101, 0x100
	s_cmpk_lt_u32 s4, 0x100
	s_cselect_b32 s100, s101, s100
	s_branch .Ls4_done
.Ls4_odd:
	s_cmpk_lt_u32 s4, 0x100
	s_cselect_b32 s100, 0x7fffffff, s101
.Ls4_done:
	s_cbranch_vccnz .LBB0_340
	s_cmpk_gt_i32 s4, 0xff
	s_cbranch_scc0 .LBB0_372
	s_cmpk_gt_u32 s4, 0x1ff
	s_cbranch_scc0 .LBB0_359
	s_add_i32 s2, s4, 0xfffffe00
	s_lshr_b32 s6, s2, 2
	s_lshl_b32 s11, s6, 8
	v_mov_b32_e32 v10, v236
	s_add_i32 s2, s11, 0x4000
	v_readlane_b32 s0, v255, 11
	v_and_b32_e32 v64, 31, v10
	v_ashrrev_i32_e32 v0, 1, v10
	v_and_b32_e32 v0, 0xffffffe0, v0
	v_or_b32_e32 v1, s2, v64
	v_readlane_b32 s1, v255, 12
	v_add_u32_e32 v206, v1, v0
	s_movk_i32 s12, 0x1200
	v_mov_b64_e32 v[0:1], s[0:1]
	v_mad_i64_i32 v[0:1], s[2:3], v206, s12, v[0:1]
	s_and_b32 s7, s4, 3
	s_lshl_b32 s3, s4, 5
	s_lshl_b32 s5, s7, 7
	s_lshl_b32 s64, s7, 8
	v_ashrrev_i32_e32 v50, 3, v10
	s_lshl_b32 s2, s6, 7
	s_and_b32 s7, s3, 64
	v_lshl_add_u64 v[8:9], v[0:1], 0, s[64:65]
	s_or_b32 s64, s7, s2
	v_ashrrev_i32_e32 v51, 31, v50
	v_lshl_add_u64 v[48:49], v[50:51], 0, s[64:65]
	v_mov_b64_e32 v[0:1], s[28:29]
	v_mad_u64_u32 v[0:1], s[2:3], v48, s12, v[0:1]
	s_lshl_b32 s2, s7, 1
	s_add_u32 s2, s9, s2
	s_addc_u32 s3, s10, 0
	s_lshl_b32 s6, s6, 11
	s_or_b32 s7, s11, 0x3800
	v_lshlrev_b32_e32 v2, 4, v10
	v_mov_b32_e32 v56, s7
	v_mov_b32_e32 v57, s6
	v_cmp_gt_i32_e32 vcc, 0, v50
	v_and_b32_e32 v208, 0x70, v2
	v_mov_b32_e32 v209, v161
	v_cndmask_b32_e32 v2, v56, v57, vcc
	s_movk_i32 s16, 0x800
	v_lshl_add_u64 v[210:211], s[2:3], 0, v[208:209]
	v_add3_u32 v2, v50, v2, s16
	v_mad_i32_i24 v1, v49, s12, v1
	v_mad_i64_i32 v[2:3], s[2:3], v2, s12, v[210:211]
	v_lshl_add_u64 v[0:1], v[0:1], 0, v[208:209]
	s_movk_i32 s2, 0x1000
	v_add_co_u32_e32 v54, vcc, s2, v0
	v_bfe_u32 v52, v10, 5, 1
	s_nop 0
	v_addc_co_u32_e32 v55, vcc, 0, v1, vcc
	global_load_dwordx4 v[0:3], v[2:3], off
	s_nop 0
	global_load_dwordx4 v[4:7], v[54:55], off
	v_lshlrev_b32_e32 v212, 4, v52
	v_mov_b32_e32 v213, v161
	v_lshl_add_u64 v[8:9], v[8:9], 0, v[212:213]
	global_load_dwordx4 v[162:165], v[8:9], off offset:512
	global_load_dwordx4 v[166:169], v[8:9], off offset:640
	global_load_dwordx4 v[170:173], v[8:9], off offset:544
	global_load_dwordx4 v[174:177], v[8:9], off offset:672
	global_load_dwordx4 v[178:181], v[8:9], off offset:576
	global_load_dwordx4 v[182:185], v[8:9], off offset:608
	global_load_dwordx4 v[186:189], v[8:9], off offset:704
	global_load_dwordx4 v[190:193], v[8:9], off offset:736
	s_movk_i32 s2, 0x90
	v_mul_lo_u32 v202, v50, s2
	v_and_b32_e32 v120, -8, v10
	v_mad_u32_u24 v65, v64, s2, 16
	v_add3_u32 v10, 16, v202, v208
	v_add_u32_e32 v53, v65, v212
	v_sub_u32_e32 v11, v10, v120
	v_add_u32_e32 v11, 0x2400, v11
	s_movk_i32 s2, 0x88
	v_lshlrev_b32_e32 v214, 3, v52
	v_mul_lo_u32 v203, v50, s2
	v_mul_u32_u24_e32 v209, 0x90, v64
	v_mul_u32_u24_e32 v213, 0x88, v64
	v_readlane_b32 s0, v255, 24
	v_readlane_b32 s1, v255, 25
	s_mov_b32 s11, 1
	v_ashrrev_i32_e32 v207, 31, v206
	s_mov_b32 s17, 0x41000000
	s_waitcnt vmcnt(9)
	ds_write_b128 v10, v[0:3]
	s_waitcnt vmcnt(8)
	ds_write2_b64 v11, v[4:5], v[6:7] offset1:1
	s_waitcnt lgkmcnt(0)
	s_barrier
	ds_read_b128 v[0:3], v53
	ds_read_b128 v[4:7], v53 offset:32
	ds_read_b128 v[8:11], v53 offset:4608
	ds_read_b128 v[12:15], v53 offset:4640
	s_waitcnt vmcnt(7) lgkmcnt(3)
	v_mfma_f32_32x32x16_bf16 v[16:31], v[0:3], v[162:165], 0
	s_waitcnt lgkmcnt(1)
	v_mfma_f32_32x32x16_bf16 v[32:47], v[8:11], v[162:165], 0
	s_waitcnt vmcnt(6)
	v_mfma_f32_32x32x16_bf16 v[88:103], v[0:3], v[166:169], 0
	v_mfma_f32_32x32x16_bf16 v[72:87], v[8:11], v[166:169], 0
	s_waitcnt vmcnt(5)
	v_mfma_f32_32x32x16_bf16 v[16:31], v[4:7], v[170:173], v[16:31]
	s_waitcnt lgkmcnt(0)
	v_mfma_f32_32x32x16_bf16 v[32:47], v[12:15], v[170:173], v[32:47]
	s_waitcnt vmcnt(4)
	v_mfma_f32_32x32x16_bf16 v[88:103], v[4:7], v[174:177], v[88:103]
	ds_read_b128 v[0:3], v53 offset:64
	ds_read_b128 v[4:7], v53 offset:96
	v_mfma_f32_32x32x16_bf16 v[72:87], v[12:15], v[174:177], v[72:87]
	ds_read_b128 v[8:11], v53 offset:4672
	ds_read_b128 v[12:15], v53 offset:4704
	v_mad_u64_u32 v[52:53], s[2:3], v48, s12, 0
	s_movk_i32 s2, 0xffc0
	s_nop 0
	v_cmp_gt_i32_e32 vcc, s2, v50
	s_movk_i32 s2, 0x840
	v_mad_i32_i24 v53, v49, s12, v53
	s_waitcnt vmcnt(3) lgkmcnt(3)
	v_mfma_f32_32x32x16_bf16 v[16:31], v[0:3], v[178:181], v[16:31]
	v_or_b32_e32 v52, v52, v208
	v_lshl_add_u64 v[218:219], s[0:1], 0, v[52:53]
	s_waitcnt lgkmcnt(1)
	v_mfma_f32_32x32x16_bf16 v[32:47], v[8:11], v[178:181], v[32:47]
	s_waitcnt vmcnt(2)
	v_mfma_f32_32x32x16_bf16 v[16:31], v[4:7], v[182:185], v[16:31]
	s_waitcnt vmcnt(1)
	v_mfma_f32_32x32x16_bf16 v[88:103], v[0:3], v[186:189], v[88:103]
	s_nop 9
	v_max_f32_e32 v2, v17, v17
	v_max_f32_e32 v3, v16, v16
	v_max_f32_e32 v2, v3, v2
	v_cndmask_b32_e32 v0, v56, v57, vcc
	v_add3_u32 v0, v50, v0, s2
	v_mad_i64_i32 v[0:1], s[2:3], v0, s12, v[210:211]
	s_waitcnt lgkmcnt(0)
	v_mfma_f32_32x32x16_bf16 v[32:47], v[12:15], v[182:185], v[32:47]
	global_load_dwordx4 v[194:197], v[0:1], off
	global_load_dwordx4 v[198:201], v[54:55], off offset:128
	s_mov_b64 s[2:3], 0x880
	v_lshl_add_u64 v[220:221], v[50:51], 0, s[2:3]
	s_waitcnt vmcnt(2)
	v_mfma_f32_32x32x16_bf16 v[88:103], v[4:7], v[190:193], v[88:103]
	s_nop 5
	v_max3_f32 v4, v18, v19, v33
	v_max3_f32 v2, v2, v32, v34
	v_max3_f32 v3, v4, v22, v23
	v_max3_f32 v2, v2, v35, v20
	v_max3_f32 v3, v3, v38, v39
	v_max3_f32 v2, v2, v21, v36
	v_max3_f32 v3, v3, v26, v27
	v_max3_f32 v2, v2, v37, v24
	v_max3_f32 v3, v3, v42, v43
	v_max3_f32 v2, v2, v25, v40
	v_max3_f32 v3, v3, v30, v31
	v_max3_f32 v2, v2, v41, v28
	v_max3_f32 v3, v3, v46, v47
	v_max3_f32 v2, v2, v29, v44
	v_max3_f32 v2, v2, v45, v3
	v_mov_b32_e32 v3, v2
	s_nop 1
	v_permlane32_swap_b32_e32 v2, v3
	v_max_f32_e32 v3, v3, v3
	v_max_f32_e32 v2, v2, v2
	v_max_f32_e32 v48, v2, v3
	v_sub_f32_e32 v16, v16, v48
	v_sub_f32_e32 v17, v17, v48
	v_sub_f32_e32 v49, v32, v48
	v_sub_f32_e32 v54, v33, v48
	v_exp_f32_e32 v32, v16
	v_exp_f32_e32 v33, v17
	v_sub_f32_e32 v18, v18, v48
	v_sub_f32_e32 v19, v19, v48
	v_exp_f32_e32 v60, v49
	v_exp_f32_e32 v61, v54
	v_sub_f32_e32 v55, v34, v48
	v_sub_f32_e32 v56, v35, v48
	v_exp_f32_e32 v34, v18
	v_exp_f32_e32 v35, v19
	v_sub_f32_e32 v20, v20, v48
	v_sub_f32_e32 v21, v21, v48
	v_exp_f32_e32 v106, v55
	v_exp_f32_e32 v107, v56
	v_sub_f32_e32 v57, v36, v48
	v_sub_f32_e32 v58, v37, v48
	v_pk_add_f32 v[16:17], v[32:33], 0 op_sel_hi:[1,0]
	v_exp_f32_e32 v36, v20
	v_exp_f32_e32 v37, v21
	v_sub_f32_e32 v22, v22, v48
	v_sub_f32_e32 v23, v23, v48
	v_pk_add_f32 v[16:17], v[60:61], v[16:17]
	v_exp_f32_e32 v108, v57
	v_exp_f32_e32 v109, v58
	v_sub_f32_e32 v59, v38, v48
	v_sub_f32_e32 v62, v39, v48
	v_pk_add_f32 v[16:17], v[34:35], v[16:17]
	v_exp_f32_e32 v38, v22
	v_exp_f32_e32 v39, v23
	v_mfma_f32_32x32x16_bf16 v[72:87], v[8:11], v[186:189], v[72:87]
	v_sub_f32_e32 v24, v24, v48
	v_sub_f32_e32 v25, v25, v48
	v_add_f32_e64 v16, v106, v16
	v_add_f32_e64 v17, v107, v17
	v_exp_f32_e32 v110, v59
	v_exp_f32_e32 v111, v62
	v_sub_f32_e32 v40, v40, v48
	v_sub_f32_e32 v41, v41, v48
	v_pk_add_f32 v[16:17], v[36:37], v[16:17]
	v_exp_f32_e32 v112, v24
	v_exp_f32_e32 v113, v25
	v_sub_f32_e32 v26, v26, v48
	v_sub_f32_e32 v27, v27, v48
	v_pk_add_f32 v[16:17], v[108:109], v[16:17]
	v_exp_f32_e32 v54, v40
	v_exp_f32_e32 v55, v41
	v_sub_f32_e32 v42, v42, v48
	v_sub_f32_e32 v43, v43, v48
	v_pk_add_f32 v[16:17], v[38:39], v[16:17]
	v_exp_f32_e32 v114, v26
	v_exp_f32_e32 v115, v27
	v_sub_f32_e32 v28, v28, v48
	v_sub_f32_e32 v29, v29, v48
	v_pk_add_f32 v[16:17], v[110:111], v[16:17]
	v_exp_f32_e32 v56, v42
	v_exp_f32_e32 v57, v43
	v_sub_f32_e32 v44, v44, v48
	v_sub_f32_e32 v45, v45, v48
	v_pk_add_f32 v[16:17], v[112:113], v[16:17]
	v_exp_f32_e32 v116, v28
	v_exp_f32_e32 v117, v29
	v_sub_f32_e32 v30, v30, v48
	v_sub_f32_e32 v31, v31, v48
	v_pk_add_f32 v[16:17], v[54:55], v[16:17]
	v_exp_f32_e32 v58, v44
	v_exp_f32_e32 v59, v45
	v_sub_f32_e32 v46, v46, v48
	v_sub_f32_e32 v47, v47, v48
	v_pk_add_f32 v[16:17], v[114:115], v[16:17]
	v_exp_f32_e32 v118, v30
	v_exp_f32_e32 v119, v31
	v_mfma_f32_32x32x16_bf16 v[72:87], v[12:15], v[190:193], v[72:87]
	v_add_f32_e64 v16, v56, v16
	v_add_f32_e64 v17, v57, v17
	v_exp_f32_e32 v62, v46
	v_exp_f32_e32 v63, v47
	v_pk_add_f32 v[16:17], v[116:117], v[16:17]
	v_max_f32_e32 v18, v88, v88
	v_pk_add_f32 v[16:17], v[58:59], v[16:17]
	v_lshlrev_b32_e32 v44, 3, v64
	v_pk_add_f32 v[16:17], v[118:119], v[16:17]
	v_sub_u32_e32 v44, v65, v44
	v_pk_add_f32 v[16:17], v[62:63], v[16:17]
	v_add_u32_e32 v44, v44, v214
	v_pk_add_f32 v[16:17], v[16:17], v[16:17] op_sel_hi:[0,1]
	v_max_f32_e32 v16, v89, v89
	v_max_f32_e32 v16, v18, v16
	v_max3_f32 v18, v90, v91, v73
	v_max3_f32 v16, v16, v72, v74
	v_max3_f32 v16, v16, v75, v92
	v_max3_f32 v18, v18, v94, v95
	v_max3_f32 v16, v16, v93, v76
	v_max3_f32 v18, v18, v78, v79
	v_max3_f32 v16, v16, v77, v96
	v_max3_f32 v18, v18, v98, v99
	v_max3_f32 v16, v16, v97, v80
	v_max3_f32 v18, v18, v82, v83
	v_max3_f32 v16, v16, v81, v100
	v_max3_f32 v18, v18, v102, v103
	v_max3_f32 v16, v16, v101, v84
	v_max3_f32 v18, v18, v86, v87
	v_max3_f32 v16, v16, v85, v18
	v_mov_b32_e32 v18, v16
	s_nop 1
	v_permlane32_swap_b32_e32 v16, v18
	v_max_f32_e32 v18, v18, v18
	v_max_f32_e32 v16, v16, v16
	v_max_f32_e32 v104, v16, v18
	v_add_u32_e32 v140, 0x2000, v44
	v_add_u32_e32 v141, 0x3000, v44
	v_sub_f32_e32 v40, v88, v104
	v_sub_f32_e32 v41, v89, v104
	v_sub_f32_e32 v42, v90, v104
	v_sub_f32_e32 v43, v91, v104
	ds_read2_b64 v[88:91], v140 offset0:128 offset1:130
	ds_read2_b64 v[122:125], v141 offset0:160 offset1:162
	v_exp_f32_e64 v2, -v48
	v_exp_f32_e64 v18, -v104
	v_sub_f32_e32 v45, v92, v104
	v_sub_f32_e32 v46, v93, v104
	v_cvt_pk_bf16_f32 v32, v32, v33
	v_cvt_pk_bf16_f32 v33, v34, v35
	v_cvt_pk_bf16_f32 v34, v36, v37
	v_sub_f32_e32 v36, v94, v104
	v_sub_f32_e32 v37, v95, v104
	v_exp_f32_e32 v126, v40
	v_exp_f32_e32 v127, v41
	v_exp_f32_e32 v128, v42
	v_exp_f32_e32 v129, v43
	v_exp_f32_e32 v130, v45
	v_exp_f32_e32 v131, v46
	v_exp_f32_e32 v132, v36
	v_exp_f32_e32 v133, v37
	v_mul_f32_e32 v0, 0, v2
	v_mov_b32_e32 v49, v0
	v_mov_b32_e32 v16, v161
	v_pk_add_f32 v[216:217], v[48:49], v[16:17]
	v_mul_f32_e32 v16, 0, v18
	v_mov_b32_e32 v1, v0
	v_mov_b32_e32 v2, v0
	v_mov_b32_e32 v3, v0
	v_mov_b32_e32 v4, v0
	v_mov_b32_e32 v5, v0
	v_mov_b32_e32 v6, v0
	v_mov_b32_e32 v7, v0
	v_mov_b32_e32 v8, v0
	v_mov_b32_e32 v9, v0
	v_mov_b32_e32 v10, v0
	v_mov_b32_e32 v11, v0
	v_mov_b32_e32 v12, v0
	v_mov_b32_e32 v13, v0
	v_mov_b32_e32 v14, v0
	v_mov_b32_e32 v15, v0
	v_pk_add_f32 v[48:49], v[216:217], 0 neg_lo:[1,1] neg_hi:[1,1]
	v_mov_b32_e32 v17, v16
	v_mov_b32_e32 v18, v16
	v_mov_b32_e32 v19, v16
	v_mov_b32_e32 v20, v16
	v_mov_b32_e32 v21, v16
	v_mov_b32_e32 v22, v16
	v_mov_b32_e32 v23, v16
	v_mov_b32_e32 v24, v16
	v_mov_b32_e32 v25, v16
	v_mov_b32_e32 v26, v16
	v_mov_b32_e32 v27, v16
	v_mov_b32_e32 v28, v16
	v_mov_b32_e32 v29, v16
	v_mov_b32_e32 v30, v16
	v_mov_b32_e32 v31, v16
	v_cvt_pk_bf16_f32 v35, v38, v39
	v_cvt_pk_bf16_f32 v92, v126, v127
	v_cvt_pk_bf16_f32 v93, v128, v129
	v_cvt_pk_bf16_f32 v94, v130, v131
	v_cvt_pk_bf16_f32 v95, v132, v133
	v_sub_f32_e32 v49, v72, v104
	v_sub_f32_e32 v121, v73, v104
	v_sub_f32_e32 v134, v74, v104
	v_sub_f32_e32 v135, v75, v104
	v_sub_f32_e32 v136, v76, v104
	v_sub_f32_e32 v137, v77, v104
	v_sub_f32_e32 v138, v78, v104
	v_sub_f32_e32 v139, v79, v104
	s_waitcnt lgkmcnt(1)
	v_mfma_f32_32x32x16_bf16 v[64:79], v[88:91], v[32:35], v[0:15]
	v_sub_f32_e32 v142, v80, v104
	v_sub_f32_e32 v80, v96, v104
	v_sub_f32_e32 v143, v97, v104
	v_sub_f32_e32 v144, v98, v104
	v_sub_f32_e32 v145, v99, v104
	ds_read2_b64 v[96:99], v141 offset0:164 offset1:166
	v_mov_b32_e32 v105, v16
	s_waitcnt lgkmcnt(1)
	v_mfma_f32_32x32x16_bf16 v[0:15], v[122:125], v[32:35], v[0:15]
	v_cvt_pk_bf16_f32 v54, v54, v55
	v_cvt_pk_bf16_f32 v55, v56, v57
	v_cvt_pk_bf16_f32 v56, v58, v59
	v_cvt_pk_bf16_f32 v57, v62, v63
	v_mov_b32_e32 v50, v48
	v_mov_b32_e32 v51, v48
	v_mov_b32_e32 v52, v48
	v_mfma_f32_32x32x16_bf16 v[32:47], v[88:91], v[92:95], v[16:31]
	ds_read2_b64 v[88:91], v140 offset0:132 offset1:134
	v_mov_b32_e32 v53, v48
	v_mfma_f32_32x32x16_bf16 v[16:31], v[122:125], v[92:95], v[16:31]
	v_sub_f32_e32 v122, v100, v104
	v_sub_f32_e32 v123, v101, v104
	v_cvt_pk_bf16_f32 v93, v114, v115
	v_sub_f32_e32 v114, v102, v104
	v_sub_f32_e32 v115, v103, v104
	v_cvt_pk_bf16_f32 v92, v112, v113
	v_exp_f32_e32 v100, v80
	v_exp_f32_e32 v101, v143
	v_exp_f32_e32 v102, v144
	v_exp_f32_e32 v103, v145
	v_exp_f32_e32 v112, v122
	v_exp_f32_e32 v113, v123
	v_exp_f32_e32 v114, v114
	v_exp_f32_e32 v115, v115
	v_cvt_pk_bf16_f32 v94, v116, v117
	v_cvt_pk_bf16_f32 v95, v118, v119
	v_sub_f32_e32 v116, v81, v104
	v_sub_f32_e32 v117, v82, v104
	s_waitcnt lgkmcnt(0)
	v_mfma_f32_32x32x16_bf16 v[64:79], v[88:91], v[92:95], v[64:79]
	v_sub_f32_e32 v118, v83, v104
	ds_read2_b64 v[80:83], v140 offset0:136 offset1:138
	v_sub_f32_e32 v119, v84, v104
	v_sub_f32_e32 v122, v85, v104
	v_exp_f32_e32 v84, v49
	v_exp_f32_e32 v85, v121
	v_sub_f32_e32 v123, v86, v104
	v_mfma_f32_32x32x16_bf16 v[0:15], v[96:99], v[92:95], v[0:15]
	v_cvt_pk_bf16_f32 v92, v100, v101
	v_cvt_pk_bf16_f32 v93, v102, v103
	v_cvt_pk_bf16_f32 v94, v112, v113
	v_cvt_pk_bf16_f32 v95, v114, v115
	v_sub_f32_e32 v49, v87, v104
	s_nop 0
	v_mfma_f32_32x32x16_bf16 v[32:47], v[88:91], v[92:95], v[32:47]
	v_cvt_pk_bf16_f32 v88, v60, v61
	v_add_f32_e64 v60, v126, 0
	v_add_f32_e64 v61, v127, 0
	v_cvt_pk_bf16_f32 v89, v106, v107
	v_cvt_pk_bf16_f32 v90, v108, v109
	v_cvt_pk_bf16_f32 v91, v110, v111
	v_pk_add_f32 v[60:61], v[84:85], v[60:61]
	v_cvt_pk_bf16_f32 v84, v84, v85
	v_mfma_f32_32x32x16_bf16 v[16:31], v[96:99], v[92:95], v[16:31]
	ds_read2_b64 v[92:95], v141 offset0:168 offset1:170
	v_exp_f32_e32 v96, v134
	v_exp_f32_e32 v97, v135
	v_exp_f32_e32 v98, v136
	v_exp_f32_e32 v99, v137
	v_pk_add_f32 v[60:61], v[128:129], v[60:61]
	v_cvt_pk_bf16_f32 v85, v96, v97
	s_waitcnt lgkmcnt(1)
	v_mfma_f32_32x32x16_bf16 v[64:79], v[80:83], v[88:91], v[64:79]
	v_add_f32_e64 v60, v96, v60
	v_add_f32_e64 v61, v97, v61
	v_cvt_pk_bf16_f32 v86, v98, v99
	v_add_f32_e64 v60, v130, v60
	v_add_f32_e64 v61, v131, v61
	v_pk_add_f32 v[60:61], v[98:99], v[60:61]
	s_nop 0
	v_pk_add_f32 v[60:61], v[132:133], v[60:61]
	s_waitcnt lgkmcnt(0)
	v_mfma_f32_32x32x16_bf16 v[0:15], v[92:95], v[88:91], v[0:15]
	v_exp_f32_e32 v88, v138
	v_exp_f32_e32 v89, v139
	v_exp_f32_e32 v90, v142
	v_exp_f32_e32 v91, v116
	v_cvt_pk_bf16_f32 v87, v88, v89
	v_pk_add_f32 v[88:89], v[88:89], v[60:61]
	s_nop 0
	v_mfma_f32_32x32x16_bf16 v[32:47], v[80:83], v[84:87], v[32:47]
	ds_read2_b64 v[80:83], v140 offset0:140 offset1:142
	ds_read2_b64 v[58:61], v141 offset0:172 offset1:174
	v_add_f32_e64 v62, v100, v88
	v_add_f32_e64 v63, v101, v89
	v_exp_f32_e32 v88, v123
	v_exp_f32_e32 v89, v49
	v_pk_add_f32 v[62:63], v[90:91], v[62:63]
	v_add3_u32 v49, 16, v203, v208
	v_mfma_f32_32x32x16_bf16 v[16:31], v[92:95], v[84:87], v[16:31]
	v_exp_f32_e32 v84, v117
	v_exp_f32_e32 v85, v118
	v_exp_f32_e32 v86, v119
	v_exp_f32_e32 v87, v122
	v_pk_add_f32 v[62:63], v[102:103], v[62:63]
	s_nop 0
	v_pk_add_f32 v[62:63], v[84:85], v[62:63]
	s_waitcnt lgkmcnt(1)
	v_mfma_f32_32x32x16_bf16 v[64:79], v[80:83], v[54:57], v[64:79]
	v_add_f32_e64 v62, v112, v62
	v_add_f32_e64 v63, v113, v63
	v_add_f32_e64 v62, v86, v62
	v_add_f32_e64 v63, v87, v63
	v_add_f32_e64 v62, v114, v62
	v_add_f32_e64 v63, v115, v63
	v_pk_add_f32 v[62:63], v[88:89], v[62:63]
	s_waitcnt lgkmcnt(0)
	v_mfma_f32_32x32x16_bf16 v[0:15], v[58:61], v[54:57], v[0:15]
	v_cvt_pk_bf16_f32 v54, v90, v91
	v_cvt_pk_bf16_f32 v55, v84, v85
	v_cvt_pk_bf16_f32 v56, v86, v87
	v_cvt_pk_bf16_f32 v57, v88, v89
	v_pk_add_f32 v[62:63], v[62:63], v[62:63] op_sel_hi:[0,1]
	v_mov_b32_e32 v62, v161
	v_pk_add_f32 v[222:223], v[104:105], v[62:63]
	v_mfma_f32_32x32x16_bf16 v[32:47], v[80:83], v[54:57], v[32:47]
	v_add_f32_e64 v80, -v222, neg(0)
	v_add_f32_e64 v81, -v223, neg(0)
	v_mov_b32_e32 v62, v48
	v_mov_b32_e32 v81, v80
	v_mov_b32_e32 v82, v80
	v_mov_b32_e32 v83, v80
	v_mov_b32_e32 v84, v80
	v_mov_b32_e32 v85, v80
	v_mfma_f32_32x32x16_bf16 v[16:31], v[58:61], v[54:57], v[16:31]
	v_add_u32_e32 v54, 0x6a00, v49
	v_add_u32_e32 v49, v49, v120
	s_waitcnt vmcnt(1)
	ds_write_b128 v49, v[194:197] offset:17920
	s_waitcnt vmcnt(0)
	ds_write2_b64 v54, v[198:199], v[200:201] offset1:1
	v_mov_b32_e32 v86, v80
	v_mov_b32_e32 v87, v80
	v_mov_b32_e32 v88, v80
	v_mov_b32_e32 v89, v80
	v_mov_b32_e32 v90, v80
	v_mov_b32_e32 v91, v80
	v_mov_b32_e32 v92, v80
	v_mov_b32_e32 v93, v80
	v_mov_b32_e32 v94, v80
	v_mov_b32_e32 v95, v80
	v_mov_b32_e32 v49, v48
	v_mov_b32_e32 v54, v48
	v_mov_b32_e32 v55, v48
	v_mov_b32_e32 v56, v48
	v_mov_b32_e32 v57, v48
	v_mov_b32_e32 v58, v48
	v_mov_b32_e32 v59, v48
	v_mov_b32_e32 v60, v48
	v_mov_b32_e32 v61, v48
	v_mov_b32_e32 v63, v48
	s_waitcnt lgkmcnt(0)
	s_barrier
	s_cmp_lt_u32 s11, 3
	s_cselect_b64 s[2:3], -1, 0
	s_cmp_gt_u32 s11, 2
	s_cbranch_scc1 .LBB0_350
